# attention loops: removed the over-draining vmcnt(3..0) ladder before the second tile's staging LDS writes (last iteration drains on its own path); QK accumulator init with v_mov_b64 pairs instead of 1
# speedup vs baseline: 1.0987x; 1.0010x over previous
.LBB0_423:
	s_lshl_b32 s16, s19, 14
	s_add_i32 s4, s16, 16
	v_add_u32_e32 v96, s4, v185
	ds_read_b128 v[198:201], v96 offset:49152
	ds_read_b128 v[202:205], v96 offset:57344
	v_xor_b32_e32 v80, 0x80000000, v195
	v_mov_b32_e32 v81, v80
	v_mov_b64_e32 v[82:83], v[80:81]
	v_mov_b64_e32 v[84:85], v[80:81]
	v_mov_b64_e32 v[86:87], v[80:81]
	v_mov_b64_e32 v[88:89], v[80:81]
	v_mov_b64_e32 v[90:91], v[80:81]
	v_mov_b64_e32 v[92:93], v[80:81]
	v_mov_b64_e32 v[94:95], v[80:81]
	v_exp_f32_e32 v221, v64
	v_add_f32_e32 v64, 0, v152
	s_waitcnt lgkmcnt(1)
	v_mfma_f32_32x32x16_bf16 v[96:111], v[198:201], v[124:127], v[80:95]
	v_add_f32_e32 v64, v153, v64
	v_add_f32_e32 v64, v154, v64
	v_add_u32_e32 v197, s4, v189
	v_add_f32_e32 v64, v155, v64
	v_add_f32_e32 v64, v156, v64
	v_add_f32_e32 v64, v157, v64
	v_add_f32_e32 v64, v158, v64
	s_waitcnt lgkmcnt(0)
	v_mfma_f32_32x32x16_bf16 v[80:95], v[202:205], v[124:127], v[80:95]
	ds_read_b128 v[198:201], v197 offset:49152
	ds_read_b128 v[202:205], v197 offset:57344
	v_add_f32_e32 v64, v159, v64
	v_add_f32_e32 v64, v144, v64
	v_add_f32_e32 v64, v145, v64
	v_add_f32_e32 v64, v146, v64
	v_add_u32_e32 v197, s4, v192
	v_add_f32_e32 v64, v147, v64
	s_waitcnt lgkmcnt(1)
	v_mfma_f32_32x32x16_bf16 v[96:111], v[198:201], v[120:123], v[96:111]
	ds_read_b128 v[198:201], v197 offset:49152
	ds_read_b128 v[206:209], v197 offset:57344
	v_add_f32_e32 v64, v148, v64
	v_exp_f32_e32 v222, v65
	v_add_f32_e32 v64, v149, v64
	v_exp_f32_e32 v223, v66
	v_add_f32_e32 v64, v150, v64
	v_exp_f32_e32 v224, v67
	s_waitcnt lgkmcnt(2)
	v_mfma_f32_32x32x16_bf16 v[80:95], v[202:205], v[120:123], v[80:95]
	v_add_f32_e32 v64, v151, v64
	v_add_f32_e32 v64, v221, v64
	v_add_f32_e32 v64, v222, v64
	v_add_f32_e32 v64, v223, v64
	v_exp_f32_e32 v71, v71
	v_add_f32_e32 v64, v224, v64
	v_add_u32_e32 v197, s4, v194
	s_waitcnt lgkmcnt(1)
	v_mfma_f32_32x32x16_bf16 v[96:111], v[198:201], v[116:119], v[96:111]
	v_exp_f32_e32 v199, v68
	v_exp_f32_e32 v200, v69
	v_exp_f32_e32 v201, v70
	v_exp_f32_e32 v225, v72
	v_add_f32_e32 v64, v199, v64
	ds_read_b128 v[202:205], v197 offset:49152
	ds_read_b128 v[210:213], v197 offset:57344
	v_exp_f32_e32 v226, v73
	s_waitcnt lgkmcnt(2)
	v_mfma_f32_32x32x16_bf16 v[80:95], v[206:209], v[116:119], v[80:95]
	v_add_f32_e32 v64, v200, v64
	v_exp_f32_e32 v227, v74
	v_add_f32_e32 v64, v201, v64
	v_exp_f32_e32 v206, v75
	v_add_f32_e32 v64, v71, v64
	v_exp_f32_e32 v207, v76
	v_add_f32_e32 v64, v225, v64
	v_exp_f32_e32 v208, v77
	v_add_f32_e32 v64, v226, v64
	v_exp_f32_e32 v209, v78
	s_waitcnt lgkmcnt(1)
	v_mfma_f32_32x32x16_bf16 v[96:111], v[202:205], v[112:115], v[96:111]
	v_add_f32_e32 v64, v227, v64
	v_exp_f32_e32 v79, v79
	v_add_f32_e32 v64, v206, v64
	v_add_f32_e32 v64, v207, v64
	v_add_f32_e32 v64, v208, v64
	v_add_f32_e32 v64, v209, v64
	v_add_f32_e32 v197, v79, v64
	s_waitcnt lgkmcnt(0)
	v_mfma_f32_32x32x16_bf16 v[80:95], v[210:213], v[112:115], v[80:95]
	v_mov_b32_e32 v198, v197
	v_cvt_pk_bf16_f32 v64, v152, v153
	v_cvt_pk_bf16_f32 v65, v154, v155
	v_cvt_pk_bf16_f32 v66, v156, v157
	v_cvt_pk_bf16_f32 v67, v158, v159
	v_cvt_pk_bf16_f32 v72, v144, v145
	v_cvt_pk_bf16_f32 v73, v146, v147
	v_cvt_pk_bf16_f32 v74, v148, v149
	v_cvt_pk_bf16_f32 v75, v150, v151
	v_cvt_pk_bf16_f32 v68, v221, v222
	v_cvt_pk_bf16_f32 v69, v223, v224
	v_cvt_pk_bf16_f32 v70, v199, v200
	v_cvt_pk_bf16_f32 v71, v201, v71
	v_cvt_pk_bf16_f32 v76, v225, v226
	v_cvt_pk_bf16_f32 v77, v227, v206
	v_cvt_pk_bf16_f32 v78, v207, v208
	v_cvt_pk_bf16_f32 v79, v209, v79
	v_permlane32_swap_b32_e32 v197, v198
	v_permlane32_swap_b32_e32 v64, v66
	v_permlane32_swap_b32_e32 v65, v67
	v_permlane32_swap_b32_e32 v72, v74
	v_permlane32_swap_b32_e32 v73, v75
	v_permlane32_swap_b32_e32 v68, v70
	v_permlane32_swap_b32_e32 v69, v71
	v_permlane32_swap_b32_e32 v76, v78
	v_permlane32_swap_b32_e32 v77, v79
	global_load_dwordx4 v[144:147], v244, s[98:99]
	global_load_dwordx4 v[148:151], v245, s[98:99]
	global_load_dwordx4 v[152:155], v242, s[98:99]
	global_load_dwordx4 v[156:159], v243, s[98:99]
	s_add_u32 s98, s98, 0x10000
	s_addc_u32 s99, s99, 0
	v_lshl_add_u32 v199, s18, 14, v181
	ds_read_b64_tr_b16 v[200:201], v199 offset:0
	ds_read_b64_tr_b16 v[202:203], v199 offset:0x800
	ds_read_b64_tr_b16 v[204:205], v199 offset:0x1000
	ds_read_b64_tr_b16 v[206:207], v199 offset:0x1800
	ds_read_b64_tr_b16 v[208:209], v199 offset:0x2000
	ds_read_b64_tr_b16 v[210:211], v199 offset:0x2800
	ds_read_b64_tr_b16 v[222:223], v199 offset:0x3000
	ds_read_b64_tr_b16 v[224:225], v199 offset:0x3800
	s_waitcnt lgkmcnt(0)
	s_nop 0
	v_mfma_f32_32x32x16_bf16 v[0:15], v[64:67], v[200:203], v[0:15]
	v_max_f32_e32 v200, v97, v97
	v_max_f32_e32 v201, v96, v96
	v_max_f32_e32 v200, v201, v200
	v_max3_f32 v200, v200, v98, v99
	v_max3_f32 v200, v200, v100, v101
	v_max3_f32 v200, v200, v102, v103
	v_max3_f32 v200, v200, v104, v105
	v_mfma_f32_32x32x16_bf16 v[0:15], v[72:75], v[204:207], v[0:15]
	v_max3_f32 v200, v200, v106, v107
	v_max3_f32 v202, v200, v108, v109
	ds_read_b64_tr_b16 v[200:201], v199 offset:0x200
	v_max3_f32 v212, v202, v110, v111
	ds_read_b64_tr_b16 v[202:203], v199 offset:0xa00
	ds_read_b64_tr_b16 v[204:205], v199 offset:0x1200
	ds_read_b64_tr_b16 v[206:207], v199 offset:0x1a00
	v_mfma_f32_32x32x16_bf16 v[0:15], v[68:71], v[208:211], v[0:15]
	ds_read_b64_tr_b16 v[208:209], v199 offset:0x2200
	ds_read_b64_tr_b16 v[210:211], v199 offset:0x2a00
	ds_read_b64_tr_b16 v[226:227], v199 offset:0x3200
	ds_read_b64_tr_b16 v[228:229], v199 offset:0x3a00
	s_waitcnt lgkmcnt(0)
	v_mfma_f32_32x32x16_bf16 v[0:15], v[76:79], v[222:225], v[0:15]
	v_mfma_f32_32x32x16_bf16 v[48:63], v[64:67], v[200:203], v[48:63]
	v_max3_f32 v212, v212, v80, v81
	v_max3_f32 v200, v212, v82, v83
	ds_read_b64_tr_b16 v[202:203], v199 offset:0x400
	v_max3_f32 v200, v200, v84, v85
	v_max3_f32 v200, v200, v86, v87
	v_max3_f32 v200, v200, v88, v89
	v_max3_f32 v200, v200, v90, v91
	v_mfma_f32_32x32x16_bf16 v[48:63], v[72:75], v[204:207], v[48:63]
	ds_read_b64_tr_b16 v[204:205], v199 offset:0xc00
	ds_read_b64_tr_b16 v[206:207], v199 offset:0x1400
	v_max3_f32 v200, v200, v92, v93
	v_max3_f32 v200, v200, v94, v95
	v_mov_b32_e32 v201, v200
	s_nop 1
	v_permlane32_swap_b32_e32 v200, v201
	v_mfma_f32_32x32x16_bf16 v[48:63], v[68:71], v[208:211], v[48:63]
	ds_read_b64_tr_b16 v[208:209], v199 offset:0x1c00
	ds_read_b64_tr_b16 v[210:211], v199 offset:0x2400
	ds_read_b64_tr_b16 v[212:213], v199 offset:0x2c00
	ds_read_b64_tr_b16 v[222:223], v199 offset:0x3400
	ds_read_b64_tr_b16 v[224:225], v199 offset:0x3c00
	s_waitcnt lgkmcnt(0)
	v_max_f32_e32 v201, v201, v201
	v_mfma_f32_32x32x16_bf16 v[48:63], v[76:79], v[226:229], v[48:63]
	v_max_f32_e32 v200, v200, v200
	v_max_f32_e32 v200, v200, v201
	v_mfma_f32_32x32x16_bf16 v[32:47], v[64:67], v[202:205], v[32:47]
	v_cmp_ge_f32_e32 vcc, s63, v200
	s_cmp_eq_u64 vcc, exec
	v_mfma_f32_32x32x16_bf16 v[32:47], v[72:75], v[206:209], v[32:47]
	v_mfma_f32_32x32x16_bf16 v[32:47], v[68:71], v[210:213], v[32:47]
	v_mfma_f32_32x32x16_bf16 v[32:47], v[76:79], v[222:225], v[32:47]
	s_cbranch_scc0 .LBB0_438
	v_mov_b32_e32 v200, 1.0

.LBB0_429:
	v_exp_f32_e32 v199, v96
	v_exp_f32_e32 v221, v97
	v_exp_f32_e32 v226, v98
	v_exp_f32_e32 v227, v99
	v_exp_f32_e32 v228, v100
	v_exp_f32_e32 v229, v101
	v_exp_f32_e32 v230, v102
	v_exp_f32_e32 v231, v103
	v_exp_f32_e32 v232, v104
	v_exp_f32_e32 v233, v105
	v_exp_f32_e32 v234, v106
	v_exp_f32_e32 v235, v107
	v_exp_f32_e32 v236, v108
	v_exp_f32_e32 v237, v109
	v_exp_f32_e32 v238, v110
	v_exp_f32_e32 v239, v111
	s_waitcnt lgkmcnt(0)
	s_barrier
	v_add_u32_e32 v96, s17, v185
	ds_read_b128 v[202:205], v96 offset:49152
	ds_read_b128 v[206:209], v96 offset:57344
	v_xor_b32_e32 v64, 0x80000000, v195
	v_mov_b32_e32 v65, v64
	v_mov_b64_e32 v[66:67], v[64:65]
	v_mov_b64_e32 v[68:69], v[64:65]
	v_mov_b64_e32 v[70:71], v[64:65]
	v_mov_b64_e32 v[72:73], v[64:65]
	v_mov_b64_e32 v[74:75], v[64:65]
	v_mov_b64_e32 v[76:77], v[64:65]
	v_mov_b64_e32 v[78:79], v[64:65]
	v_add_u32_e32 v201, s17, v189
	v_exp_f32_e32 v80, v80
	s_waitcnt lgkmcnt(1)
	v_mfma_f32_32x32x16_bf16 v[96:111], v[202:205], v[124:127], v[64:79]
	v_exp_f32_e32 v81, v81
	v_exp_f32_e32 v82, v82
	v_exp_f32_e32 v83, v83
	v_exp_f32_e32 v84, v84
	v_exp_f32_e32 v85, v85
	v_exp_f32_e32 v86, v86
	v_exp_f32_e32 v87, v87
	s_waitcnt lgkmcnt(0)
	v_mfma_f32_32x32x16_bf16 v[64:79], v[206:209], v[124:127], v[64:79]
	ds_read_b128 v[202:205], v201 offset:49152
	ds_read_b128 v[206:209], v201 offset:57344
	v_add_u32_e32 v201, s17, v192
	v_exp_f32_e32 v240, v91
	v_exp_f32_e32 v241, v92
	v_cvt_pk_bf16_f32 v91, v230, v231
	v_cvt_pk_bf16_f32 v92, v232, v233
	s_waitcnt lgkmcnt(1)
	v_mfma_f32_32x32x16_bf16 v[96:111], v[202:205], v[120:123], v[96:111]
	ds_read_b128 v[202:205], v201 offset:49152
	ds_read_b128 v[210:213], v201 offset:57344
	v_add_u32_e32 v201, s17, v194
	s_waitcnt lgkmcnt(1)
	v_mfma_f32_32x32x16_bf16 v[96:111], v[202:205], v[116:119], v[96:111]
	v_exp_f32_e32 v203, v88
	v_add_f32_e32 v88, 0, v199
	v_add_f32_e32 v88, v221, v88
	v_add_f32_e32 v88, v226, v88
	v_add_f32_e32 v88, v227, v88
	v_add_f32_e32 v88, v228, v88
	v_add_f32_e32 v88, v229, v88
	v_add_f32_e32 v88, v230, v88
	v_add_f32_e32 v88, v231, v88
	v_add_f32_e32 v88, v232, v88
	v_add_f32_e32 v88, v233, v88
	v_mfma_f32_32x32x16_bf16 v[64:79], v[206:209], v[120:123], v[64:79]
	v_add_f32_e32 v88, v234, v88
	v_add_f32_e32 v88, v235, v88
	v_add_f32_e32 v88, v236, v88
	v_add_f32_e32 v88, v237, v88
	v_add_f32_e32 v88, v238, v88
	v_add_f32_e32 v88, v239, v88
	v_add_f32_e32 v88, v80, v88
	v_add_f32_e32 v88, v81, v88
	s_waitcnt lgkmcnt(0)
	v_mfma_f32_32x32x16_bf16 v[64:79], v[210:213], v[116:119], v[64:79]
	v_add_f32_e32 v88, v82, v88
	v_add_f32_e32 v88, v83, v88
	v_add_f32_e32 v88, v84, v88
	ds_read_b128 v[206:209], v201 offset:49152
	ds_read_b128 v[222:225], v201 offset:57344
	v_exp_f32_e32 v204, v89
	v_add_f32_e32 v88, v85, v88
	v_exp_f32_e32 v205, v90
	v_add_f32_e32 v88, v86, v88
	v_add_f32_e32 v88, v87, v88
	v_add_f32_e32 v88, v203, v88
	v_exp_f32_e32 v210, v93
	v_add_f32_e32 v88, v204, v88
	v_exp_f32_e32 v211, v94
	s_waitcnt lgkmcnt(1)
	v_mfma_f32_32x32x16_bf16 v[96:111], v[206:209], v[112:115], v[96:111]
	v_add_f32_e32 v88, v205, v88
	v_exp_f32_e32 v212, v95
	v_add_f32_e32 v88, v240, v88
	v_add_f32_e32 v88, v241, v88
	v_add_f32_e32 v88, v210, v88
	v_add_f32_e32 v88, v211, v88
	v_add_f32_e32 v201, v212, v88
	s_waitcnt lgkmcnt(0)
	v_mfma_f32_32x32x16_bf16 v[64:79], v[222:225], v[112:115], v[64:79]
	v_mov_b32_e32 v202, v201
	v_cvt_pk_bf16_f32 v88, v199, v221
	v_cvt_pk_bf16_f32 v89, v226, v227
	v_cvt_pk_bf16_f32 v90, v228, v229
	v_cvt_pk_bf16_f32 v93, v234, v235
	v_cvt_pk_bf16_f32 v94, v236, v237
	v_cvt_pk_bf16_f32 v95, v238, v239
	v_cvt_pk_bf16_f32 v80, v80, v81
	v_cvt_pk_bf16_f32 v81, v82, v83
	v_cvt_pk_bf16_f32 v82, v84, v85
	v_cvt_pk_bf16_f32 v83, v86, v87
	v_cvt_pk_bf16_f32 v84, v203, v204
	v_cvt_pk_bf16_f32 v85, v205, v240
	v_cvt_pk_bf16_f32 v86, v241, v210
	v_cvt_pk_bf16_f32 v87, v211, v212
	v_permlane32_swap_b32_e32 v201, v202
	v_permlane32_swap_b32_e32 v88, v90
	v_permlane32_swap_b32_e32 v89, v91
	v_permlane32_swap_b32_e32 v92, v94
	v_permlane32_swap_b32_e32 v93, v95
	v_permlane32_swap_b32_e32 v80, v82
	v_permlane32_swap_b32_e32 v81, v83
	v_permlane32_swap_b32_e32 v84, v86
	v_permlane32_swap_b32_e32 v85, v87
	s_cmpk_gt_u32 s6, 0x7c
	s_cselect_b64 s[4:5], -1, 0
	s_and_b64 vcc, exec, s[4:5]
	s_cbranch_vccnz .Lattn_a0_lastw
	global_load_dwordx4 v[132:135], v244, s[98:99]
	global_load_dwordx4 v[128:131], v242, s[98:99]
	global_load_dwordx4 v[140:143], v245, s[98:99]
	global_load_dwordx4 v[136:139], v243, s[98:99]
	s_add_u32 s98, s98, 0x10000
	s_addc_u32 s99, s99, 0

.LBB0_432:
	ds_read_b64_tr_b16 v[204:205], v203 offset:0x600
	ds_read_b64_tr_b16 v[206:207], v203 offset:0xe00
	ds_read_b64_tr_b16 v[208:209], v203 offset:0x1600
	ds_read_b64_tr_b16 v[210:211], v203 offset:0x1e00
	ds_read_b64_tr_b16 v[222:223], v203 offset:0x2600
	ds_read_b64_tr_b16 v[224:225], v203 offset:0x2e00
	ds_read_b64_tr_b16 v[226:227], v203 offset:0x3600
	ds_read_b64_tr_b16 v[228:229], v203 offset:0x3e00
	s_add_i32 s16, s18, 1
	s_waitcnt lgkmcnt(0)
	s_cmp_lg_u32 s18, 2
	s_cselect_b32 s19, s16, 0
	v_mfma_f32_32x32x16_bf16 v[16:31], v[88:91], v[204:207], v[16:31]
	s_lshl_b32 s16, s19, 14
	s_add_i32 s16, s16, 16
	s_waitcnt vmcnt(4)
	v_add_u32_e32 v88, s16, v184
	ds_write_b128 v88, v[144:147]
	v_cmp_gt_f32_e32 vcc, 1.0, v199
	v_mfma_f32_32x32x16_bf16 v[16:31], v[92:95], v[208:211], v[16:31]
	v_mfma_f32_32x32x16_bf16 v[16:31], v[80:83], v[222:225], v[16:31]
	v_add_u32_e32 v80, s16, v186
	ds_write_b128 v80, v[148:151]
	v_add_u32_e32 v80, s16, v183
	ds_write_b128 v80, v[152:155] offset:49152
	v_add_u32_e32 v80, s16, v188
	ds_write_b128 v80, v[156:159] offset:49152
	v_mfma_f32_32x32x16_bf16 v[16:31], v[84:87], v[226:229], v[16:31]
	s_cbranch_vccz .LBB0_436
	s_and_saveexec_b64 s[16:17], s[0:1]
	ds_write_b32 v179, v199 offset:128
	s_or_b64 exec, exec, s[16:17]
	s_waitcnt lgkmcnt(0)
	v_add_u32_e32 v92, v177, v176
	ds_read_b128 v[80:83], v92 offset:224
	ds_read_b128 v[84:87], v92 offset:192
	ds_read_b128 v[88:91], v92 offset:160
	ds_read_b128 v[92:95], v92 offset:128
	s_waitcnt lgkmcnt(3)
	v_pk_mul_f32 v[12:13], v[12:13], v[80:81]
	s_waitcnt lgkmcnt(2)
	v_pk_mul_f32 v[8:9], v[8:9], v[84:85]
	s_waitcnt lgkmcnt(1)
	v_pk_mul_f32 v[4:5], v[4:5], v[88:89]
	v_pk_mul_f32 v[14:15], v[14:15], v[82:83]
	v_pk_mul_f32 v[10:11], v[10:11], v[86:87]
	v_pk_mul_f32 v[6:7], v[6:7], v[90:91]
	s_waitcnt lgkmcnt(0)
	v_pk_mul_f32 v[2:3], v[2:3], v[94:95]
	v_pk_mul_f32 v[0:1], v[0:1], v[92:93]
	v_pk_mul_f32 v[60:61], v[60:61], v[80:81]
	v_pk_mul_f32 v[56:57], v[56:57], v[84:85]
	v_pk_mul_f32 v[52:53], v[52:53], v[88:89]
	v_pk_mul_f32 v[62:63], v[62:63], v[82:83]
	v_pk_mul_f32 v[58:59], v[58:59], v[86:87]
	v_pk_mul_f32 v[54:55], v[54:55], v[90:91]
	v_pk_mul_f32 v[50:51], v[50:51], v[94:95]
	v_pk_mul_f32 v[48:49], v[48:49], v[92:93]
	v_pk_mul_f32 v[44:45], v[44:45], v[80:81]
	v_pk_mul_f32 v[40:41], v[40:41], v[84:85]
	v_pk_mul_f32 v[36:37], v[36:37], v[88:89]
	v_pk_mul_f32 v[46:47], v[46:47], v[82:83]
	v_pk_mul_f32 v[42:43], v[42:43], v[86:87]
	v_pk_mul_f32 v[38:39], v[38:39], v[90:91]
	v_pk_mul_f32 v[34:35], v[34:35], v[94:95]
	v_pk_mul_f32 v[32:33], v[32:33], v[92:93]
	v_pk_mul_f32 v[28:29], v[28:29], v[80:81]
	v_pk_mul_f32 v[24:25], v[24:25], v[84:85]
	v_pk_mul_f32 v[20:21], v[20:21], v[88:89]
	v_pk_mul_f32 v[30:31], v[30:31], v[82:83]
	v_pk_mul_f32 v[26:27], v[26:27], v[86:87]
	v_pk_mul_f32 v[22:23], v[22:23], v[90:91]
	v_pk_mul_f32 v[18:19], v[18:19], v[94:95]
	v_pk_mul_f32 v[16:17], v[16:17], v[92:93]

.Lattn_a0_lastw:
	s_waitcnt vmcnt(0)
	s_branch .LBB0_431

.LBB0_440:
	v_or_b32_e32 v136, 0x2000, v190
	v_add_u32_e32 v90, s58, v185
	v_add3_u32 v96, v182, v136, s58
	ds_read_b128 v[128:131], v90
	ds_read_b128 v[132:135], v96
	v_xor_b32_e32 v80, 0x80000000, v195
	v_mov_b32_e32 v81, v80
	v_mov_b64_e32 v[82:83], v[80:81]
	v_mov_b64_e32 v[84:85], v[80:81]
	v_mov_b64_e32 v[86:87], v[80:81]
	v_mov_b64_e32 v[88:89], v[80:81]
	v_mov_b64_e32 v[90:91], v[80:81]
	v_mov_b64_e32 v[92:93], v[80:81]
	v_mov_b64_e32 v[94:95], v[80:81]
	v_exp_f32_e32 v137, v65
	v_exp_f32_e32 v138, v70
	s_waitcnt lgkmcnt(1)
	v_mfma_f32_32x32x16_bf16 v[96:111], v[128:131], v[124:127], v[80:95]
	v_add3_u32 v128, v187, v136, s58
	ds_read_b128 v[128:131], v128
	v_exp_f32_e32 v139, v71
	v_exp_f32_e32 v140, v72
	v_exp_f32_e32 v79, v79
	v_cvt_pk_bf16_f32 v65, v154, v155
	v_cvt_pk_bf16_f32 v70, v148, v149
	s_waitcnt lgkmcnt(1)
	v_mfma_f32_32x32x16_bf16 v[80:95], v[132:135], v[124:127], v[80:95]
	v_add_u32_e32 v124, s58, v189
	ds_read_b128 v[124:127], v124
	v_add3_u32 v132, v191, v136, s58
	v_cvt_pk_bf16_f32 v71, v150, v151
	s_waitcnt lgkmcnt(0)
	v_mfma_f32_32x32x16_bf16 v[96:111], v[124:127], v[120:123], v[96:111]
	v_add_u32_e32 v124, s58, v192
	ds_read_b128 v[124:127], v124
	v_mfma_f32_32x32x16_bf16 v[80:95], v[128:131], v[120:123], v[80:95]
	ds_read_b128 v[120:123], v132
	v_add3_u32 v132, v193, v136, s58
	v_exp_f32_e32 v136, v64
	v_add_f32_e32 v64, 0, v152
	v_add_f32_e32 v64, v153, v64
	v_add_f32_e32 v64, v154, v64
	v_add_f32_e32 v64, v155, v64
	v_add_f32_e32 v64, v156, v64
	v_add_f32_e32 v64, v157, v64
	v_add_f32_e32 v64, v158, v64
	v_add_f32_e32 v64, v159, v64
	v_add_f32_e32 v64, v144, v64
	v_add_f32_e32 v64, v145, v64
	v_add_f32_e32 v64, v146, v64
	v_add_f32_e32 v64, v147, v64
	v_add_f32_e32 v64, v148, v64
	v_add_f32_e32 v64, v149, v64
	s_waitcnt lgkmcnt(1)
	v_mfma_f32_32x32x16_bf16 v[96:111], v[124:127], v[116:119], v[96:111]
	v_exp_f32_e32 v124, v66
	v_add_f32_e32 v64, v150, v64
	v_exp_f32_e32 v125, v67
	v_add_f32_e32 v64, v151, v64
	v_exp_f32_e32 v126, v68
	v_add_f32_e32 v64, v136, v64
	v_exp_f32_e32 v127, v69
	v_add_f32_e32 v64, v137, v64
	s_waitcnt lgkmcnt(0)
	v_mfma_f32_32x32x16_bf16 v[80:95], v[120:123], v[116:119], v[80:95]
	v_add_f32_e32 v64, v124, v64
	v_add_f32_e32 v64, v125, v64
	v_add_u32_e32 v128, s58, v194
	v_add_f32_e32 v64, v126, v64
	ds_read_b128 v[128:131], v128
	ds_read_b128 v[132:135], v132
	v_exp_f32_e32 v116, v73
	v_add_f32_e32 v64, v127, v64
	v_exp_f32_e32 v117, v74
	v_add_f32_e32 v64, v138, v64
	v_exp_f32_e32 v118, v75
	v_add_f32_e32 v64, v139, v64
	v_exp_f32_e32 v119, v76
	v_add_f32_e32 v64, v140, v64
	v_exp_f32_e32 v120, v77
	v_add_f32_e32 v64, v116, v64
	v_exp_f32_e32 v121, v78
	s_waitcnt lgkmcnt(1)
	v_mfma_f32_32x32x16_bf16 v[96:111], v[128:131], v[112:115], v[96:111]
	v_add_f32_e32 v64, v117, v64
	v_add_f32_e32 v64, v118, v64
	v_add_f32_e32 v64, v119, v64
	v_add_f32_e32 v64, v120, v64
	v_add_f32_e32 v64, v121, v64
	v_cvt_pk_bf16_f32 v66, v156, v157
	v_cvt_pk_bf16_f32 v67, v158, v159
	s_waitcnt lgkmcnt(0)
	v_mfma_f32_32x32x16_bf16 v[80:95], v[132:135], v[112:115], v[80:95]
	v_add_f32_e32 v112, v79, v64
	v_mov_b32_e32 v113, v112
	v_cvt_pk_bf16_f32 v64, v152, v153
	v_cvt_pk_bf16_f32 v68, v144, v145
	v_cvt_pk_bf16_f32 v69, v146, v147
	v_cvt_pk_bf16_f32 v72, v136, v137
	v_cvt_pk_bf16_f32 v73, v124, v125
	v_cvt_pk_bf16_f32 v74, v126, v127
	v_cvt_pk_bf16_f32 v75, v138, v139
	v_cvt_pk_bf16_f32 v76, v140, v116
	v_cvt_pk_bf16_f32 v77, v117, v118
	v_cvt_pk_bf16_f32 v78, v119, v120
	v_cvt_pk_bf16_f32 v79, v121, v79
	v_permlane32_swap_b32_e32 v112, v113
	v_permlane32_swap_b32_e32 v64, v66
	v_permlane32_swap_b32_e32 v65, v67
	v_permlane32_swap_b32_e32 v68, v70
	v_permlane32_swap_b32_e32 v69, v71
	v_permlane32_swap_b32_e32 v72, v74
	v_permlane32_swap_b32_e32 v73, v75
	v_permlane32_swap_b32_e32 v76, v78
	v_permlane32_swap_b32_e32 v77, v79
	ds_read_b64_tr_b16 v[114:115], v181 offset:0
	ds_read_b64_tr_b16 v[116:117], v181 offset:0x800
	ds_read_b64_tr_b16 v[118:119], v181 offset:0x1000
	ds_read_b64_tr_b16 v[120:121], v181 offset:0x1800
	ds_read_b64_tr_b16 v[122:123], v181 offset:0x2000
	ds_read_b64_tr_b16 v[124:125], v181 offset:0x2800
	ds_read_b64_tr_b16 v[126:127], v181 offset:0x3000
	ds_read_b64_tr_b16 v[128:129], v181 offset:0x3800
	s_waitcnt lgkmcnt(0)
	s_nop 0
	v_mfma_f32_32x32x16_bf16 v[0:15], v[64:67], v[114:117], v[0:15]
	v_max_f32_e32 v114, v97, v97
	v_max_f32_e32 v115, v96, v96
	v_max_f32_e32 v114, v115, v114
	v_max3_f32 v114, v114, v98, v99
	v_max3_f32 v114, v114, v100, v101
	v_max3_f32 v114, v114, v102, v103
	v_max3_f32 v114, v114, v104, v105
	v_mfma_f32_32x32x16_bf16 v[0:15], v[68:71], v[118:121], v[0:15]
	v_max3_f32 v114, v114, v106, v107
	v_max3_f32 v116, v114, v108, v109
	ds_read_b64_tr_b16 v[114:115], v181 offset:0x200
	v_max3_f32 v134, v116, v110, v111
	ds_read_b64_tr_b16 v[116:117], v181 offset:0xa00
	ds_read_b64_tr_b16 v[118:119], v181 offset:0x1200
	ds_read_b64_tr_b16 v[120:121], v181 offset:0x1a00
	v_mfma_f32_32x32x16_bf16 v[0:15], v[72:75], v[122:125], v[0:15]
	ds_read_b64_tr_b16 v[122:123], v181 offset:0x2200
	ds_read_b64_tr_b16 v[124:125], v181 offset:0x2a00
	ds_read_b64_tr_b16 v[130:131], v181 offset:0x3200
	ds_read_b64_tr_b16 v[132:133], v181 offset:0x3a00
	s_waitcnt lgkmcnt(0)
	v_mfma_f32_32x32x16_bf16 v[0:15], v[76:79], v[126:129], v[0:15]
	v_mfma_f32_32x32x16_bf16 v[48:63], v[64:67], v[114:117], v[48:63]
	v_max3_f32 v126, v134, v80, v81
	v_max3_f32 v114, v126, v82, v83
	ds_read_b64_tr_b16 v[116:117], v181 offset:0x400
	v_max3_f32 v114, v114, v84, v85
	v_max3_f32 v114, v114, v86, v87
	v_max3_f32 v114, v114, v88, v89
	v_max3_f32 v114, v114, v90, v91
	v_mfma_f32_32x32x16_bf16 v[48:63], v[68:71], v[118:121], v[48:63]
	ds_read_b64_tr_b16 v[118:119], v181 offset:0xc00
	ds_read_b64_tr_b16 v[120:121], v181 offset:0x1400
	v_max3_f32 v114, v114, v92, v93
	v_max3_f32 v114, v114, v94, v95
	v_mov_b32_e32 v115, v114
	s_nop 1
	v_permlane32_swap_b32_e32 v114, v115
	v_mfma_f32_32x32x16_bf16 v[48:63], v[72:75], v[122:125], v[48:63]
	ds_read_b64_tr_b16 v[122:123], v181 offset:0x1c00
	ds_read_b64_tr_b16 v[124:125], v181 offset:0x2400
	ds_read_b64_tr_b16 v[126:127], v181 offset:0x2c00
	ds_read_b64_tr_b16 v[134:135], v181 offset:0x3400
	ds_read_b64_tr_b16 v[136:137], v181 offset:0x3c00
	s_waitcnt lgkmcnt(0)
	v_max_f32_e32 v115, v115, v115
	v_mfma_f32_32x32x16_bf16 v[48:63], v[76:79], v[130:133], v[48:63]
	v_max_f32_e32 v114, v114, v114
	v_max_f32_e32 v115, v114, v115
	v_mfma_f32_32x32x16_bf16 v[32:47], v[64:67], v[116:119], v[32:47]
	v_cmp_ge_f32_e32 vcc, s63, v115
	s_cmp_eq_u64 vcc, exec
	v_mov_b32_e32 v114, 1.0
	v_mfma_f32_32x32x16_bf16 v[32:47], v[68:71], v[120:123], v[32:47]
	v_mfma_f32_32x32x16_bf16 v[32:47], v[72:75], v[124:127], v[32:47]
	v_mfma_f32_32x32x16_bf16 v[32:47], v[76:79], v[134:137], v[32:47]
	s_cbranch_scc0 .LBB0_451
